# final output stores (out = RMSNorm(...)) written through (sc0 sc1) so the end-of-kernel L2 write-back has nothing left to flush
# speedup vs baseline: 1.0081x; 1.0081x over previous
;     __device__ __forceinline__ void fused(f32x4 (&acc)[2][2][4][2], const Unit& u, int wr, int wc, int fr, int fq, PG8_LAS unsigned char* lds, int wid, int lane) const {
;     ...
; #pragma unroll
;         for (int bj = 0; bj < 2; ++bj)
; #pragma unroll
;             for (int n = 0; n < 2; ++n) { const f32x4 w4 = *(const f32x4*)(fw + col0 + bj * HALF + n * 16);
; #pragma unroll
;                 for (int ai = 0; ai < 2; ++ai)
; #pragma unroll
;                     for (int m = 0; m < 4; ++m) { const int rl = ai * HALF + wr * 64 + m * 16 + fr; const float rs = Sr[rl];
;                         *(f32x4*)(out + (size_t)(u.pm * BM + rl) * 1024 + col0 + bj * HALF + n * 16) = acc[ai][bj][m][n] * rs * w4; } }
.LBB0_1122:
	s_or_b64 exec, exec, s[4:5]
	v_readlane_b32 s0, v239, 12
	v_lshlrev_b64 v[146:147], 2, v[130:131]
	v_readlane_b32 s14, v239, 26
	v_readlane_b32 s15, v239, 27
	s_waitcnt lgkmcnt(0)
	s_barrier
	v_readlane_b32 s1, v239, 13
	v_lshl_add_u64 v[130:131], s[14:15], 0, v[146:147]
	global_load_dwordx4 v[154:157], v[130:131], off
	v_readlane_b32 s2, v239, 14
	v_readlane_b32 s3, v239, 15
	v_readlane_b32 s0, v239, 1
	v_lshl_add_u32 v166, v148, 2, 0
	v_readlane_b32 s1, v239, 2
	v_add_u32_e32 v166, 0x1000, v166
	v_readlane_b32 s4, v239, 16
	v_lshl_add_u64 v[128:129], s[0:1], 0, v[128:129]
	v_lshl_add_u64 v[148:149], s[0:1], 0, v[132:133]
	v_lshl_add_u64 v[150:151], s[0:1], 0, v[134:135]
	v_lshl_add_u64 v[152:153], s[0:1], 0, v[136:137]
	v_lshl_add_u64 v[158:159], s[0:1], 0, v[138:139]
	v_lshl_add_u64 v[160:161], s[0:1], 0, v[140:141]
	v_lshl_add_u64 v[162:163], s[0:1], 0, v[142:143]
	v_lshl_add_u64 v[164:165], s[0:1], 0, v[144:145]
	v_lshl_add_u64 v[132:133], v[128:129], 0, v[146:147]
	v_lshl_add_u64 v[134:135], v[148:149], 0, v[146:147]
	v_lshl_add_u64 v[136:137], v[150:151], 0, v[146:147]
	v_lshl_add_u64 v[138:139], v[152:153], 0, v[146:147]
	v_lshl_add_u64 v[140:141], v[158:159], 0, v[146:147]
	v_lshl_add_u64 v[142:143], v[160:161], 0, v[146:147]
	v_lshl_add_u64 v[144:145], v[162:163], 0, v[146:147]
	ds_read2_b32 v[152:153], v166 offset1:16
	v_lshl_add_u64 v[128:129], v[164:165], 0, v[146:147]
	ds_read2_b32 v[150:151], v166 offset0:32 offset1:48
	ds_read2_b32 v[148:149], v166 offset0:128 offset1:144
	ds_read2_b32 v[146:147], v166 offset0:160 offset1:176
	v_readlane_b32 s5, v239, 17
	v_readlane_b32 s6, v239, 18
	s_waitcnt lgkmcnt(3)
	v_pk_mul_f32 v[158:159], v[124:125], v[152:153] op_sel_hi:[1,0]
	v_pk_mul_f32 v[126:127], v[126:127], v[152:153] op_sel_hi:[1,0]
	v_mov_b32_e32 v124, v153
	s_waitcnt lgkmcnt(2)
	v_pk_mul_f32 v[160:161], v[92:93], v[150:151] op_sel_hi:[1,0]
	v_mov_b32_e32 v92, v151
	s_waitcnt lgkmcnt(1)
	v_pk_mul_f32 v[162:163], v[60:61], v[148:149] op_sel_hi:[1,0]
	v_mov_b32_e32 v60, v149
	s_waitcnt lgkmcnt(0)
	v_pk_mul_f32 v[166:167], v[28:29], v[146:147] op_sel_hi:[1,0]
	v_mov_b32_e32 v28, v147
	v_pk_mul_f32 v[94:95], v[94:95], v[150:151] op_sel_hi:[1,0]
	v_pk_mul_f32 v[62:63], v[62:63], v[148:149] op_sel_hi:[1,0]
	v_pk_mul_f32 v[30:31], v[30:31], v[146:147] op_sel_hi:[1,0]
	v_pk_mul_f32 v[108:109], v[108:109], v[124:125] op_sel_hi:[1,0]
	v_pk_mul_f32 v[110:111], v[110:111], v[124:125] op_sel_hi:[1,0]
	v_pk_mul_f32 v[164:165], v[76:77], v[92:93] op_sel_hi:[1,0]
	v_pk_mul_f32 v[168:169], v[78:79], v[92:93] op_sel_hi:[1,0]
	v_pk_mul_f32 v[170:171], v[44:45], v[60:61] op_sel_hi:[1,0]
	v_pk_mul_f32 v[172:173], v[46:47], v[60:61] op_sel_hi:[1,0]
	v_pk_mul_f32 v[174:175], v[12:13], v[28:29] op_sel_hi:[1,0]
	v_pk_mul_f32 v[176:177], v[14:15], v[28:29] op_sel_hi:[1,0]
	v_pk_mul_f32 v[56:57], v[56:57], v[148:149] op_sel_hi:[1,0]
	v_pk_mul_f32 v[58:59], v[58:59], v[148:149] op_sel_hi:[1,0]
	v_pk_mul_f32 v[72:73], v[72:73], v[92:93] op_sel_hi:[1,0]
	v_pk_mul_f32 v[74:75], v[74:75], v[92:93] op_sel_hi:[1,0]
	v_pk_mul_f32 v[32:33], v[32:33], v[60:61] op_sel_hi:[1,0]
	v_pk_mul_f32 v[34:35], v[34:35], v[60:61] op_sel_hi:[1,0]
	v_readlane_b32 s7, v239, 19
	v_readlane_b32 s8, v239, 20
	v_readlane_b32 s9, v239, 21
	v_readlane_b32 s10, v239, 22
	v_readlane_b32 s11, v239, 23
	v_readlane_b32 s12, v239, 24
	v_readlane_b32 s13, v239, 25
	v_readlane_b32 s2, v239, 3
	v_readlane_b32 s3, v239, 4
	s_waitcnt vmcnt(0)
	v_pk_mul_f32 v[14:15], v[156:157], v[126:127]
	v_pk_mul_f32 v[12:13], v[154:155], v[158:159]
	v_pk_mul_f32 v[46:47], v[156:157], v[110:111]
	v_pk_mul_f32 v[44:45], v[154:155], v[108:109]
	v_pk_mul_f32 v[78:79], v[156:157], v[94:95]
	v_pk_mul_f32 v[76:77], v[154:155], v[160:161]
	v_pk_mul_f32 v[110:111], v[156:157], v[168:169]
	v_pk_mul_f32 v[108:109], v[154:155], v[164:165]
	v_pk_mul_f32 v[160:161], v[156:157], v[62:63]
	v_pk_mul_f32 v[158:159], v[154:155], v[162:163]
	v_pk_mul_f32 v[164:165], v[156:157], v[172:173]
	v_pk_mul_f32 v[162:163], v[154:155], v[170:171]
	v_pk_mul_f32 v[168:169], v[156:157], v[30:31]
	v_pk_mul_f32 v[166:167], v[154:155], v[166:167]
	v_pk_mul_f32 v[156:157], v[156:157], v[176:177]
	v_pk_mul_f32 v[154:155], v[154:155], v[174:175]
	global_store_dwordx4 v[132:133], v[12:15], off sc0 sc1
	global_store_dwordx4 v[134:135], v[44:47], off sc0 sc1
	global_store_dwordx4 v[136:137], v[76:79], off sc0 sc1
	global_store_dwordx4 v[138:139], v[108:111], off sc0 sc1
	global_store_dwordx4 v[140:141], v[158:161], off sc0 sc1
	global_store_dwordx4 v[142:143], v[162:165], off sc0 sc1
	global_store_dwordx4 v[144:145], v[166:169], off sc0 sc1
	global_store_dwordx4 v[128:129], v[154:157], off sc0 sc1
	global_load_dwordx4 v[12:15], v[130:131], off offset:64
	v_pk_mul_f32 v[30:31], v[120:121], v[152:153] op_sel_hi:[1,0]
	v_pk_mul_f32 v[44:45], v[122:123], v[152:153] op_sel_hi:[1,0]
	v_pk_mul_f32 v[46:47], v[88:89], v[150:151] op_sel_hi:[1,0]
	v_pk_mul_f32 v[62:63], v[90:91], v[150:151] op_sel_hi:[1,0]
	v_pk_mul_f32 v[76:77], v[24:25], v[146:147] op_sel_hi:[1,0]
	v_pk_mul_f32 v[78:79], v[26:27], v[146:147] op_sel_hi:[1,0]
	v_pk_mul_f32 v[24:25], v[104:105], v[124:125] op_sel_hi:[1,0]
	v_pk_mul_f32 v[26:27], v[106:107], v[124:125] op_sel_hi:[1,0]
	v_pk_mul_f32 v[88:89], v[40:41], v[60:61] op_sel_hi:[1,0]
	v_pk_mul_f32 v[90:91], v[42:43], v[60:61] op_sel_hi:[1,0]
	v_pk_mul_f32 v[94:95], v[8:9], v[28:29] op_sel_hi:[1,0]
	v_pk_mul_f32 v[104:105], v[10:11], v[28:29] op_sel_hi:[1,0]
	s_waitcnt vmcnt(0)
;     __device__ __forceinline__ void fused(f32x4 (&acc)[2][2][4][2], const Unit& u, int wr, int wc, int fr, int fq, PG8_LAS unsigned char* lds, int wid, int lane) const {
;     ...
; #pragma unroll
;         for (int bj = 0; bj < 2; ++bj)
; #pragma unroll
;             for (int n = 0; n < 2; ++n) { const f32x4 w4 = *(const f32x4*)(fw + col0 + bj * HALF + n * 16);
; #pragma unroll
;                 for (int ai = 0; ai < 2; ++ai)
; #pragma unroll
;                     for (int m = 0; m < 4; ++m) { const int rl = ai * HALF + wr * 64 + m * 16 + fr; const float rs = Sr[rl];
;                         *(f32x4*)(out + (size_t)(u.pm * BM + rl) * 1024 + col0 + bj * HALF + n * 16) = acc[ai][bj][m][n] * rs * w4; } }
	v_pk_mul_f32 v[10:11], v[14:15], v[44:45]
	v_pk_mul_f32 v[8:9], v[12:13], v[30:31]
	v_pk_mul_f32 v[26:27], v[14:15], v[26:27]
	v_pk_mul_f32 v[24:25], v[12:13], v[24:25]
	v_pk_mul_f32 v[42:43], v[14:15], v[62:63]
	v_pk_mul_f32 v[40:41], v[12:13], v[46:47]
	v_pk_mul_f32 v[46:47], v[14:15], v[74:75]
	v_pk_mul_f32 v[44:45], v[12:13], v[72:73]
	v_pk_mul_f32 v[58:59], v[14:15], v[58:59]
	v_pk_mul_f32 v[56:57], v[12:13], v[56:57]
	v_pk_mul_f32 v[74:75], v[14:15], v[90:91]
	v_pk_mul_f32 v[72:73], v[12:13], v[88:89]
	v_pk_mul_f32 v[78:79], v[14:15], v[78:79]
	v_pk_mul_f32 v[76:77], v[12:13], v[76:77]
	v_pk_mul_f32 v[14:15], v[14:15], v[104:105]
	v_pk_mul_f32 v[12:13], v[12:13], v[94:95]
	global_store_dwordx4 v[132:133], v[8:11], off offset:64 sc0 sc1
	global_store_dwordx4 v[134:135], v[24:27], off offset:64 sc0 sc1
	global_store_dwordx4 v[136:137], v[40:43], off offset:64 sc0 sc1
	global_store_dwordx4 v[138:139], v[44:47], off offset:64 sc0 sc1
	global_store_dwordx4 v[140:141], v[56:59], off offset:64 sc0 sc1
	global_store_dwordx4 v[142:143], v[72:75], off offset:64 sc0 sc1
	global_store_dwordx4 v[144:145], v[76:79], off offset:64 sc0 sc1
	global_store_dwordx4 v[128:129], v[12:15], off offset:64 sc0 sc1
	global_load_dwordx4 v[8:11], v[130:131], off offset:512
	v_pk_mul_f32 v[24:25], v[84:85], v[150:151] op_sel_hi:[1,0]
	v_pk_mul_f32 v[12:13], v[116:117], v[152:153] op_sel_hi:[1,0]
	v_pk_mul_f32 v[14:15], v[118:119], v[152:153] op_sel_hi:[1,0]
	v_pk_mul_f32 v[26:27], v[86:87], v[150:151] op_sel_hi:[1,0]
	v_pk_mul_f32 v[30:31], v[52:53], v[148:149] op_sel_hi:[1,0]
	v_pk_mul_f32 v[40:41], v[54:55], v[148:149] op_sel_hi:[1,0]
	v_pk_mul_f32 v[44:45], v[20:21], v[146:147] op_sel_hi:[1,0]
	v_pk_mul_f32 v[46:47], v[22:23], v[146:147] op_sel_hi:[1,0]
	v_pk_mul_f32 v[20:21], v[100:101], v[124:125] op_sel_hi:[1,0]
	v_pk_mul_f32 v[22:23], v[102:103], v[124:125] op_sel_hi:[1,0]
	v_pk_mul_f32 v[42:43], v[68:69], v[92:93] op_sel_hi:[1,0]
	v_pk_mul_f32 v[52:53], v[70:71], v[92:93] op_sel_hi:[1,0]
	v_pk_mul_f32 v[54:55], v[36:37], v[60:61] op_sel_hi:[1,0]
	v_pk_mul_f32 v[56:57], v[38:39], v[60:61] op_sel_hi:[1,0]
	v_pk_mul_f32 v[58:59], v[4:5], v[28:29] op_sel_hi:[1,0]
	v_pk_mul_f32 v[62:63], v[6:7], v[28:29] op_sel_hi:[1,0]
	s_waitcnt vmcnt(0)
	v_pk_mul_f32 v[6:7], v[14:15], v[10:11]
	v_pk_mul_f32 v[4:5], v[12:13], v[8:9]
	v_pk_mul_f32 v[14:15], v[22:23], v[10:11]
	v_pk_mul_f32 v[12:13], v[20:21], v[8:9]
	v_pk_mul_f32 v[22:23], v[26:27], v[10:11]
	v_pk_mul_f32 v[20:21], v[24:25], v[8:9]
	v_pk_mul_f32 v[26:27], v[52:53], v[10:11]
	v_pk_mul_f32 v[24:25], v[42:43], v[8:9]
	v_pk_mul_f32 v[38:39], v[40:41], v[10:11]
	v_pk_mul_f32 v[36:37], v[30:31], v[8:9]
	v_pk_mul_f32 v[42:43], v[56:57], v[10:11]
	v_pk_mul_f32 v[40:41], v[54:55], v[8:9]
	v_pk_mul_f32 v[46:47], v[46:47], v[10:11]
	v_pk_mul_f32 v[44:45], v[44:45], v[8:9]
	v_pk_mul_f32 v[10:11], v[10:11], v[62:63]
	v_pk_mul_f32 v[8:9], v[8:9], v[58:59]
	global_store_dwordx4 v[132:133], v[4:7], off offset:512 sc0 sc1
	global_store_dwordx4 v[134:135], v[12:15], off offset:512 sc0 sc1
	global_store_dwordx4 v[136:137], v[20:23], off offset:512 sc0 sc1
	global_store_dwordx4 v[138:139], v[24:27], off offset:512 sc0 sc1
	global_store_dwordx4 v[140:141], v[36:39], off offset:512 sc0 sc1
	global_store_dwordx4 v[142:143], v[40:43], off offset:512 sc0 sc1
	global_store_dwordx4 v[144:145], v[44:47], off offset:512 sc0 sc1
	global_store_dwordx4 v[128:129], v[8:11], off offset:512 sc0 sc1
	global_load_dwordx4 v[4:7], v[130:131], off offset:576
	v_pk_mul_f32 v[12:13], v[80:81], v[150:151] op_sel_hi:[1,0]
	v_pk_mul_f32 v[8:9], v[112:113], v[152:153] op_sel_hi:[1,0]
	v_pk_mul_f32 v[10:11], v[114:115], v[152:153] op_sel_hi:[1,0]
	v_pk_mul_f32 v[14:15], v[82:83], v[150:151] op_sel_hi:[1,0]
	v_pk_mul_f32 v[20:21], v[48:49], v[148:149] op_sel_hi:[1,0]
	v_pk_mul_f32 v[22:23], v[50:51], v[148:149] op_sel_hi:[1,0]
	v_pk_mul_f32 v[36:37], v[16:17], v[146:147] op_sel_hi:[1,0]
	v_pk_mul_f32 v[30:31], v[18:19], v[146:147] op_sel_hi:[1,0]
	v_pk_mul_f32 v[16:17], v[96:97], v[124:125] op_sel_hi:[1,0]
	v_pk_mul_f32 v[18:19], v[98:99], v[124:125] op_sel_hi:[1,0]
	v_pk_mul_f32 v[24:25], v[64:65], v[92:93] op_sel_hi:[1,0]
	v_pk_mul_f32 v[26:27], v[66:67], v[92:93] op_sel_hi:[1,0]
	v_pk_mul_f32 v[38:39], v[0:1], v[28:29] op_sel_hi:[1,0]
	v_pk_mul_f32 v[40:41], v[2:3], v[28:29] op_sel_hi:[1,0]
	s_waitcnt vmcnt(0)
	v_pk_mul_f32 v[2:3], v[10:11], v[6:7]
	v_pk_mul_f32 v[0:1], v[8:9], v[4:5]
	v_pk_mul_f32 v[10:11], v[18:19], v[6:7]
	v_pk_mul_f32 v[8:9], v[16:17], v[4:5]
	v_pk_mul_f32 v[14:15], v[14:15], v[6:7]
	v_pk_mul_f32 v[12:13], v[12:13], v[4:5]
	v_pk_mul_f32 v[18:19], v[26:27], v[6:7]
	v_pk_mul_f32 v[16:17], v[24:25], v[4:5]
	v_pk_mul_f32 v[22:23], v[22:23], v[6:7]
	v_pk_mul_f32 v[20:21], v[20:21], v[4:5]
	v_pk_mul_f32 v[26:27], v[34:35], v[6:7]
	v_pk_mul_f32 v[24:25], v[32:33], v[4:5]
	v_pk_mul_f32 v[30:31], v[30:31], v[6:7]
	v_pk_mul_f32 v[28:29], v[36:37], v[4:5]
	v_pk_mul_f32 v[6:7], v[40:41], v[6:7]
	v_pk_mul_f32 v[4:5], v[38:39], v[4:5]
	global_store_dwordx4 v[132:133], v[0:3], off offset:576 sc0 sc1
	global_store_dwordx4 v[134:135], v[8:11], off offset:576 sc0 sc1
	global_store_dwordx4 v[136:137], v[12:15], off offset:576 sc0 sc1
	global_store_dwordx4 v[138:139], v[16:19], off offset:576 sc0 sc1
	global_store_dwordx4 v[140:141], v[20:23], off offset:576 sc0 sc1
	global_store_dwordx4 v[142:143], v[24:27], off offset:576 sc0 sc1
	global_store_dwordx4 v[144:145], v[28:31], off offset:576 sc0 sc1
	global_store_dwordx4 v[128:129], v[4:7], off offset:576 sc0 sc1
	s_endpgm
